# P1 row loop: next row's scale/shift parameter loads issued one iteration ahead (moved at the latch)
# speedup vs baseline: 1.0077x; 1.0077x over previous
.LBB0_207:
	s_or_b64 exec, exec, s[0:1]
	v_readlane_b32 s0, v247, 2
	v_readlane_b32 s1, v247, 3
	v_readlane_b32 s0, v247, 0
	v_readlane_b32 s6, v247, 8
	s_lshl_b32 s18, s0, 2
	s_lshl_b32 s30, s6, 2
	v_add_u32_e32 v132, s18, v129
	s_mov_b32 s19, 0x8000
	v_add_u32_e32 v138, s30, v132
	v_readlane_b32 s1, v247, 1
	v_cmp_gt_i32_e64 s[34:35], s19, v132
	v_ashrrev_i32_e32 v133, 31, v132
	v_mbcnt_lo_u32_b32 v192, -1, 0
	v_ashrrev_i32_e32 v139, 31, v138
	s_waitcnt lgkmcnt(0)
	s_barrier
	v_readlane_b32 s2, v247, 4
	v_readlane_b32 s3, v247, 5
	v_readlane_b32 s4, v247, 6
	v_readlane_b32 s5, v247, 7
	v_readlane_b32 s7, v247, 9
	s_and_saveexec_b64 s[0:1], s[34:35]
	s_cbranch_execz .LBB0_214
	v_readlane_b32 s36, v247, 13
	v_readlane_b32 s37, v247, 14
	v_lshlrev_b64 v[0:1], 12, v[132:133]
	s_mov_b64 s[12:13], s[36:37]
	v_lshl_add_u64 v[0:1], s[12:13], 0, v[0:1]
	v_lshlrev_b32_e32 v40, 4, v128
	v_mov_b32_e32 v41, 0
	v_lshl_add_u64 v[0:1], v[0:1], 0, v[40:41]
	global_load_dwordx4 v[24:27], v[0:1], off
	global_load_dwordx4 v[20:23], v[0:1], off offset:1024
	global_load_dwordx4 v[28:31], v[0:1], off offset:2048
	s_nop 0
	global_load_dwordx4 v[0:3], v[0:1], off offset:3072
	v_mbcnt_hi_u32_b32 v4, -1, v192
	v_and_b32_e32 v6, 64, v4
	v_xor_b32_e32 v5, 16, v4
	v_add_u32_e32 v6, 64, v6
	v_cmp_lt_i32_e32 vcc, v5, v6
	v_lshlrev_b64 v[12:13], 10, v[132:133]
	v_readlane_b32 s44, v247, 21
	v_cndmask_b32_e32 v5, v4, v5, vcc
	v_lshlrev_b32_e32 v62, 2, v5
	v_xor_b32_e32 v5, 32, v4
	v_cmp_lt_i32_e32 vcc, v5, v6
	v_readlane_b32 s45, v247, 22
	v_readlane_b32 s46, v247, 23
	v_cndmask_b32_e32 v4, v4, v5, vcc
	v_lshlrev_b32_e32 v63, 2, v4
	v_lshlrev_b32_e32 v4, 2, v128
	v_or_b32_e32 v12, v12, v4
	v_lshl_add_u64 v[46:47], s[64:65], 0, v[12:13]
	v_lshlrev_b64 v[12:13], 12, v[138:139]
	v_readlane_b32 s47, v247, 24
	v_readlane_b32 s48, v247, 25
	v_readlane_b32 s49, v247, 26
	v_readlane_b32 s50, v247, 27
	v_readlane_b32 s51, v247, 28
	s_mov_b64 s[20:21], s[44:45]
	v_or_b32_e32 v6, 0x100, v4
	v_or_b32_e32 v8, 0x200, v4
	v_or_b32_e32 v10, 0x300, v4
	s_ashr_i32 s31, s30, 31
	v_or_b32_e32 v12, v12, v40
	v_cmp_eq_u32_e64 s[6:7], 0, v128
	v_lshl_add_u64 v[42:43], s[20:21], 0, v[40:41]
	v_lshl_add_u64 v[44:45], v[132:133], 2, s[54:55]
	s_lshl_b64 s[2:3], s[30:31], 2
	s_lshl_b64 s[4:5], s[30:31], 10
	v_lshl_add_u64 v[48:49], s[12:13], 0, v[12:13]
	s_lshl_b64 s[12:13], s[30:31], 12
	s_mov_b64 s[14:15], 0
	v_mov_b32_e32 v64, 0x358637bd
	v_lshlrev_b32_e32 v40, 2, v4
	v_lshlrev_b32_e32 v50, 2, v6
	v_mov_b32_e32 v51, v41
	v_lshlrev_b32_e32 v52, 2, v8
	v_mov_b32_e32 v53, v41
	v_lshlrev_b32_e32 v54, 2, v10
	v_mov_b32_e32 v55, v41
	s_mov_b32 s20, 0x43600000
	v_mov_b32_e32 v32, v132
	v_readlane_b32 s38, v247, 15
	v_readlane_b32 s39, v247, 16
	v_readlane_b32 s40, v247, 17
	v_readlane_b32 s41, v247, 18
	v_readlane_b32 s42, v247, 19
	v_readlane_b32 s43, v247, 20
	s_mov_b64 s[22:23], s[46:47]
	s_mov_b64 s[24:25], s[48:49]
	s_mov_b64 s[26:27], s[50:51]
	s_waitcnt vmcnt(3)
	v_mov_b32_e32 v35, v27
	s_waitcnt vmcnt(2)
	v_mov_b32_e32 v34, v23
	s_waitcnt vmcnt(1)
	v_mov_b32_e32 v57, v31
	s_waitcnt vmcnt(0)
	v_mov_b32_e32 v56, v3
	v_mov_b32_e32 v3, v30
	v_mov_b32_e32 v58, v1
	v_mov_b32_e32 v59, v29
	v_mov_b32_e32 v1, v28
	v_mov_b32_e32 v23, v26
	v_mov_b32_e32 v36, v21
	v_mov_b32_e32 v37, v25
	v_mov_b32_e32 v21, v24
	global_load_dwordx4 v[76:79], v[42:43], off
	global_load_dwordx4 v[80:83], v[42:43], off offset:1024
	global_load_dwordx4 v[84:87], v[42:43], off offset:2048
	global_load_dwordx4 v[88:91], v[42:43], off offset:3072
	v_ashrrev_i32_e32 v178, 11, v32
	v_mul_i32_i24_e32 v178, 0x1800, v178
	s_mov_b64 s[10:11], 0x1000
	v_ashrrev_i32_e32 v179, 31, v178
	v_lshl_add_u64 v[178:179], v[178:179], 2, s[86:87]
	v_lshl_add_u64 v[180:181], v[178:179], 0, v[40:41]
	v_lshl_add_u64 v[178:179], v[178:179], 0, s[10:11]
	v_lshl_add_u64 v[182:183], v[178:179], 0, v[40:41]
	v_lshl_add_u64 v[184:185], v[178:179], 0, v[50:51]
	v_lshl_add_u64 v[186:187], v[178:179], 0, v[52:53]
	v_lshl_add_u64 v[188:189], v[178:179], 0, v[54:55]
	global_load_dwordx4 v[92:95], v[182:183], off
	global_load_dwordx4 v[96:99], v[184:185], off
	global_load_dwordx4 v[100:103], v[186:187], off
	global_load_dwordx4 v[104:107], v[188:189], off
	global_load_dwordx4 v[108:111], v[180:181], off
	global_load_dwordx4 v[112:115], v[180:181], off offset:1024
	global_load_dwordx4 v[116:119], v[180:181], off offset:2048
	global_load_dwordx4 v[120:123], v[180:181], off offset:3072
	s_waitcnt vmcnt(0)
	s_branch .LBB0_210
.LBB0_209:
	s_waitcnt vmcnt(4)
	s_or_b64 exec, exec, s[16:17]
	v_mov_b32_e32 v92, v144
	v_mov_b32_e32 v93, v145
	v_mov_b32_e32 v94, v146
	v_mov_b32_e32 v95, v147
	v_mov_b32_e32 v96, v148
	v_mov_b32_e32 v97, v149
	v_mov_b32_e32 v98, v150
	v_mov_b32_e32 v99, v151
	v_mov_b32_e32 v100, v152
	v_mov_b32_e32 v101, v153
	v_mov_b32_e32 v102, v154
	v_mov_b32_e32 v103, v155
	v_mov_b32_e32 v104, v156
	v_mov_b32_e32 v105, v157
	v_mov_b32_e32 v106, v158
	v_mov_b32_e32 v107, v159
	v_mov_b32_e32 v108, v160
	v_mov_b32_e32 v109, v161
	v_mov_b32_e32 v110, v162
	v_mov_b32_e32 v111, v163
	v_mov_b32_e32 v112, v164
	v_mov_b32_e32 v113, v165
	v_mov_b32_e32 v114, v166
	v_mov_b32_e32 v115, v167
	v_mov_b32_e32 v116, v168
	v_mov_b32_e32 v117, v169
	v_mov_b32_e32 v118, v170
	v_mov_b32_e32 v119, v171
	v_mov_b32_e32 v120, v172
	v_mov_b32_e32 v121, v173
	v_mov_b32_e32 v122, v174
	v_mov_b32_e32 v123, v175
	s_and_b64 s[8:9], exec, s[8:9]
	s_or_b64 s[14:15], s[8:9], s[14:15]
	v_lshl_add_u64 v[44:45], v[44:45], 0, s[2:3]
	v_lshl_add_u64 v[46:47], v[46:47], 0, s[4:5]
	v_lshl_add_u64 v[48:49], v[48:49], 0, s[12:13]
	v_mov_b32_e32 v32, v65
	v_mov_b32_e32 v56, v19
	v_mov_b32_e32 v57, v15
	v_mov_b32_e32 v2, v18
	v_mov_b32_e32 v3, v14
	v_mov_b32_e32 v58, v17
	v_mov_b32_e32 v59, v13
	v_mov_b32_e32 v0, v16
	v_mov_b32_e32 v1, v12
	v_mov_b32_e32 v34, v11
	v_mov_b32_e32 v35, v7
	v_mov_b32_e32 v22, v10
	v_mov_b32_e32 v23, v6
	v_mov_b32_e32 v36, v9
	v_mov_b32_e32 v37, v5
	v_mov_b32_e32 v20, v8
	v_mov_b32_e32 v21, v4
	s_andn2_b64 exec, exec, s[14:15]
	s_cbranch_execz .LBB0_214
.LBB0_210:
	v_add_u32_e32 v65, s30, v32
	s_movk_i32 s8, 0x7fff
	v_cmp_gt_i32_e32 vcc, s19, v65
	v_cmp_lt_i32_e64 s[8:9], s8, v65
	s_nop 0
	v_cndmask_b32_e32 v176, v32, v65, vcc
	v_ashrrev_i32_e32 v24, 11, v176
	v_mul_i32_i24_e32 v24, 0x1800, v24
	s_mov_b64 s[10:11], 0x1000
	v_ashrrev_i32_e32 v25, 31, v24
	v_lshl_add_u64 v[24:25], v[24:25], 2, s[86:87]
	v_lshl_add_u64 v[32:33], v[24:25], 0, s[10:11]
	v_lshl_add_u64 v[60:61], v[24:25], 0, v[40:41]
	v_lshl_add_u64 v[26:27], v[32:33], 0, v[40:41]
	v_lshl_add_u64 v[28:29], v[32:33], 0, v[50:51]
	v_lshl_add_u64 v[30:31], v[32:33], 0, v[52:53]
	v_lshl_add_u64 v[32:33], v[32:33], 0, v[54:55]
	global_load_dwordx4 v[144:147], v[26:27], off
	global_load_dwordx4 v[148:151], v[28:29], off
	global_load_dwordx4 v[152:155], v[30:31], off
	global_load_dwordx4 v[156:159], v[32:33], off
	global_load_dwordx4 v[160:163], v[60:61], off
	global_load_dwordx4 v[164:167], v[60:61], off offset:1024
	global_load_dwordx4 v[168:171], v[60:61], off offset:2048
	global_load_dwordx4 v[172:175], v[60:61], off offset:3072
	s_sub_u32 s24, 0, s12
	s_subb_u32 s25, 0, s13
	v_lshl_add_u64 v[124:125], v[48:49], 0, s[24:25]
	v_cndmask_b32_e32 v126, v124, v48, vcc
	v_cndmask_b32_e32 v127, v125, v49, vcc
	global_load_dwordx4 v[4:7], v[126:127], off
	global_load_dwordx4 v[8:11], v[126:127], off offset:1024
	global_load_dwordx4 v[12:15], v[126:127], off offset:2048
	global_load_dwordx4 v[16:19], v[126:127], off offset:3072
	v_pk_mul_f32 v[24:25], v[20:21], v[20:21]
	v_pk_mul_f32 v[26:27], v[0:1], v[0:1]
	v_pk_fma_f32 v[24:25], v[36:37], v[36:37], v[24:25]
	v_pk_fma_f32 v[26:27], v[58:59], v[58:59], v[26:27]
	v_pk_fma_f32 v[24:25], v[22:23], v[22:23], v[24:25]
	v_pk_fma_f32 v[26:27], v[2:3], v[2:3], v[26:27]
	v_pk_fma_f32 v[24:25], v[34:35], v[34:35], v[24:25]
	v_pk_fma_f32 v[26:27], v[56:57], v[56:57], v[26:27]
	v_add_f32_e32 v24, v24, v25
	v_add_f32_e32 v24, v27, v24
	v_add_f32_e32 v24, v26, v24
	s_mov_b32 s10, 0x800000
	v_add_f32_dpp v24, v24, v24 row_ror:8 row_mask:0xf bank_mask:0xf bound_ctrl:1
	s_nop 1
	v_add_f32_dpp v24, v24, v24 row_ror:4 row_mask:0xf bank_mask:0xf bound_ctrl:1
	s_nop 1
	v_add_f32_dpp v24, v24, v24 row_ror:2 row_mask:0xf bank_mask:0xf bound_ctrl:1
	s_nop 1
	v_add_f32_dpp v24, v24, v24 row_ror:1 row_mask:0xf bank_mask:0xf bound_ctrl:1
	s_nop 1
	v_mov_b32_e32 v25, v24
	s_nop 1
	v_permlane16_swap_b32_e32 v25, v24
	s_nop 1
	v_add_f32_e32 v24, v24, v25
	s_nop 1
	v_mov_b32_e32 v25, v24
	s_nop 1
	v_permlane32_swap_b32_e32 v25, v24
	s_nop 1
	v_add_f32_e32 v24, v24, v25
	v_fmamk_f32 v24, v24, 0x3a800000, v64
	v_cmp_gt_f32_e32 vcc, s10, v24
	v_mul_f32_e32 v25, 0x4b800000, v24
	v_cndmask_b32_e32 v24, v24, v25, vcc
	v_rsq_f32_e32 v24, v24
	s_nop 0
	v_mul_f32_e32 v25, 0x45800000, v24
	v_cndmask_b32_e32 v66, v24, v25, vcc
	v_mul_f32_e32 v142, v21, v66
	v_add_f32_e32 v143, 1.0, v92
	v_mul_f32_e32 v142, v76, v142
	v_fma_f32 v24, v143, v142, v108
	v_mul_f32_e32 v142, v37, v66
	v_add_f32_e32 v143, 1.0, v93
	v_mul_f32_e32 v142, v77, v142
	v_fma_f32 v25, v143, v142, v109
	v_mul_f32_e32 v142, v23, v66
	v_add_f32_e32 v143, 1.0, v94
	v_mul_f32_e32 v142, v78, v142
	v_fma_f32 v26, v143, v142, v110
	v_mul_f32_e32 v142, v35, v66
	v_add_f32_e32 v143, 1.0, v95
	v_mul_f32_e32 v142, v79, v142
	v_fma_f32 v27, v143, v142, v111
	v_mul_f32_e32 v142, v20, v66
	v_add_f32_e32 v143, 1.0, v96
	v_mul_f32_e32 v142, v80, v142
	v_fma_f32 v28, v143, v142, v112
	v_mul_f32_e32 v142, v36, v66
	v_add_f32_e32 v143, 1.0, v97
	v_mul_f32_e32 v142, v81, v142
	v_fma_f32 v67, v143, v142, v113
	v_mul_f32_e32 v142, v22, v66
	v_add_f32_e32 v143, 1.0, v98
	v_mul_f32_e32 v142, v82, v142
	v_fma_f32 v29, v143, v142, v114
	v_mul_f32_e32 v142, v34, v66
	v_add_f32_e32 v143, 1.0, v99
	v_mul_f32_e32 v142, v83, v142
	v_fma_f32 v31, v143, v142, v115
	v_mul_f32_e32 v142, v1, v66
	v_add_f32_e32 v143, 1.0, v100
	v_mul_f32_e32 v142, v84, v142
	v_fma_f32 v1, v143, v142, v116
	v_mul_f32_e32 v142, v59, v66
	v_add_f32_e32 v143, 1.0, v101
	v_mul_f32_e32 v142, v85, v142
	v_fma_f32 v59, v143, v142, v117
	v_mul_f32_e32 v142, v3, v66
	v_add_f32_e32 v143, 1.0, v102
	v_mul_f32_e32 v142, v86, v142
	v_fma_f32 v3, v143, v142, v118
	v_mul_f32_e32 v142, v57, v66
	v_add_f32_e32 v143, 1.0, v103
	v_mul_f32_e32 v142, v87, v142
	v_fma_f32 v23, v143, v142, v119
	v_mul_f32_e32 v142, v0, v66
	v_add_f32_e32 v143, 1.0, v104
	v_mul_f32_e32 v142, v88, v142
	v_fma_f32 v20, v143, v142, v120
	v_mul_f32_e32 v142, v58, v66
	v_add_f32_e32 v143, 1.0, v105
	v_mul_f32_e32 v142, v89, v142
	v_fma_f32 v21, v143, v142, v121
	v_mul_f32_e32 v142, v2, v66
	v_add_f32_e32 v143, 1.0, v106
	v_mul_f32_e32 v142, v90, v142
	v_fma_f32 v2, v143, v142, v122
	v_mul_f32_e32 v142, v56, v66
	v_add_f32_e32 v143, 1.0, v107
	v_mul_f32_e32 v142, v91, v142
	v_fma_f32 v35, v143, v142, v123
	v_max_f32_e64 v30, |v26|, |v27|
	v_max3_f32 v30, |v24|, |v25|, v30
	v_max3_f32 v30, |v28|, |v67|, v30
	v_max3_f32 v30, |v29|, |v31|, v30
	v_max3_f32 v30, |v1|, |v59|, v30
	v_max3_f32 v30, |v3|, |v23|, v30
	v_max3_f32 v30, |v20|, |v21|, v30
	v_max3_f32 v0, |v2|, |v35|, v30
	s_nop 1
	v_mov_b32_dpp v22, v0 row_ror:8 row_mask:0xf bank_mask:0xf bound_ctrl:1
	v_max_f32_e32 v22, v22, v22
	v_max_f32_e32 v0, v0, v22
	s_nop 1
	v_mov_b32_dpp v22, v0 row_ror:4 row_mask:0xf bank_mask:0xf bound_ctrl:1
	v_max_f32_e32 v22, v22, v22
	v_max_f32_e32 v0, v0, v22
	s_nop 1
	v_mov_b32_dpp v22, v0 row_ror:2 row_mask:0xf bank_mask:0xf bound_ctrl:1
	v_max_f32_e32 v22, v22, v22
	v_max_f32_e32 v0, v0, v22
	s_nop 1
	v_mov_b32_dpp v22, v0 row_ror:1 row_mask:0xf bank_mask:0xf bound_ctrl:1
	v_max_f32_e32 v22, v22, v22
	v_max_f32_e32 v0, v0, v22
	s_nop 1
	v_mov_b32_e32 v22, v0
	s_nop 1
	v_permlane16_swap_b32_e32 v22, v0
	s_nop 1
	v_max_f32_e32 v0, v0, v22
	s_nop 1
	v_mov_b32_e32 v22, v0
	s_nop 1
	v_permlane32_swap_b32_e32 v22, v0
	s_nop 1
	v_max_f32_e32 v0, v0, v22
	v_div_scale_f32 v22, s[16:17], v0, v0, s20
	v_rcp_f32_e32 v30, v22
	v_cmp_lt_f32_e64 s[10:11], 0, v0
	v_fma_f32 v32, -v22, v30, 1.0
	v_fmac_f32_e32 v30, v32, v30
	v_div_scale_f32 v32, vcc, s20, v0, s20
	v_mul_f32_e32 v33, v32, v30
	v_fma_f32 v34, -v22, v33, v32
	v_fmac_f32_e32 v33, v34, v30
	v_fma_f32 v22, -v22, v33, v32
	v_div_fmas_f32 v22, v22, v30, v33
	v_div_fixup_f32 v22, v22, v0, s20
	v_cndmask_b32_e64 v22, 1.0, v22, s[10:11]
	v_mul_f32_e32 v24, v24, v22
	v_mul_f32_e32 v25, v25, v22
	v_mov_b32_e32 v30, 0
	v_cvt_pk_fp8_f32 v30, v24, v25
	v_mul_f32_e32 v24, v26, v22
	v_mul_f32_e32 v25, v27, v22
	v_mov_b32_e32 v26, 0
	v_cvt_pk_fp8_f32 v30, v24, v25 op_sel:[0,0,1]
	v_mul_f32_e32 v24, v28, v22
	v_mul_f32_e32 v25, v67, v22
	v_cvt_pk_fp8_f32 v26, v24, v25
	v_mul_f32_e32 v24, v29, v22
	v_mul_f32_e32 v25, v31, v22
	v_mul_f32_e32 v1, v1, v22
	v_cvt_pk_fp8_f32 v26, v24, v25 op_sel:[0,0,1]
	v_mul_f32_e32 v24, v59, v22
	v_mov_b32_e32 v25, 0
	v_cvt_pk_fp8_f32 v25, v1, v24
	v_mul_f32_e32 v1, v3, v22
	v_mul_f32_e32 v3, v23, v22
	global_store_dword v[46:47], v30, off
	v_cvt_pk_fp8_f32 v25, v1, v3 op_sel:[0,0,1]
	v_mul_f32_e32 v1, v20, v22
	v_mul_f32_e32 v3, v21, v22
	v_mov_b32_e32 v20, 0
	v_cvt_pk_fp8_f32 v20, v1, v3
	v_mul_f32_e32 v1, v2, v22
	v_mul_f32_e32 v2, v35, v22
	global_store_dword v[46:47], v26, off offset:256
	v_cvt_pk_fp8_f32 v20, v1, v2 op_sel:[0,0,1]
	global_store_dword v[46:47], v25, off offset:512
	global_store_dword v[46:47], v20, off offset:768
	s_and_saveexec_b64 s[16:17], s[6:7]
	s_cbranch_execz .LBB0_209
	v_mul_f32_e32 v0, 0x3b924925, v0
	v_cndmask_b32_e64 v0, 1.0, v0, s[10:11]
	global_store_dword v[44:45], v0, off
	s_branch .LBB0_209
